# mode-0 attention unit epilogue: all 16 sub-LN gain loads issued up front by the st==0 waves before the LDS exchange barrier (into free VGPRs) instead of 16 serialized load-wait-store round trips
# speedup vs baseline: 1.0045x; 1.0045x over previous
; __device__ __forceinline__ float swapsum(float m) { auto rr = __builtin_amdgcn_permlane32_swap(__float_as_uint(m), __float_as_uint(m), false, false); return __uint_as_float(rr[0]) + __uint_as_float(rr[1]); }
; template <int MODE> __device__ __forceinline__ void attn_unit4(LAS unsigned char* lds, const int uidx, const AttnArgs& A) {
;     ...
;         if (st == 0) {
;             const float sx = wave_sum(A.dl[lane] * A.dl[64 + lane], lane), sy = wave_sum(A.dl[128 + lane] * A.dl[192 + lane], lane);
;             const float lam = __expf(sx) - __expf(sy) + A.lam_init;
;             float ss = 0.f;
; #pragma unroll
;             for (int d = 0; d < NDB; ++d)
; #pragma unroll
;                 for (int r = 0; r < 16; ++r) { const float v = o[d][r] - lam * X[(qg * 64 + d * 16 + r) * 64 + lane]; o[d][r] = v; ss += v * v; }
;             ss = swapsum(ss);
.LBB0_1005:
	s_cmpk_gt_u32 s30, 0xff
	s_waitcnt lgkmcnt(0)
	s_barrier
	s_cbranch_scc1 .LBB0_908
	v_lshlrev_b32_e32 v0, 2, v177
	s_lshl_b32 s0, s30, 8
	v_add_u32_e32 v0, 0, v0
	s_and_b32 s1, s0, 0xc000
	s_or_b32 s0, s0, 0x3f00
	v_mov_b32_e32 v14, v251
	v_add_u32_e32 v4, s1, v0
	v_add_u32_e32 v0, s0, v0
	ds_read2st64_b32 v[132:133], v4 offset1:1
	ds_read2st64_b32 v[134:135], v4 offset0:2 offset1:3
	ds_read2st64_b32 v[128:129], v4 offset0:4 offset1:5
	ds_read2st64_b32 v[130:131], v4 offset0:6 offset1:7
	ds_read2st64_b32 v[124:125], v4 offset0:8 offset1:9
	ds_read2st64_b32 v[126:127], v4 offset0:10 offset1:11
	ds_read2st64_b32 v[120:121], v4 offset0:12 offset1:13
	ds_read2st64_b32 v[122:123], v4 offset0:14 offset1:15
	ds_read2st64_b32 v[116:117], v4 offset0:16 offset1:17
	ds_read2st64_b32 v[118:119], v4 offset0:18 offset1:19
	ds_read2st64_b32 v[112:113], v4 offset0:20 offset1:21
	ds_read2st64_b32 v[114:115], v4 offset0:22 offset1:23
	ds_read2st64_b32 v[108:109], v4 offset0:24 offset1:25
	ds_read2st64_b32 v[110:111], v4 offset0:26 offset1:27
	ds_read2st64_b32 v[104:105], v4 offset0:28 offset1:29
	ds_read2st64_b32 v[106:107], v4 offset0:30 offset1:31
	ds_read2st64_b32 v[100:101], v4 offset0:32 offset1:33
	ds_read2st64_b32 v[102:103], v4 offset0:34 offset1:35
	ds_read2st64_b32 v[96:97], v4 offset0:36 offset1:37
	ds_read2st64_b32 v[98:99], v4 offset0:38 offset1:39
	ds_read2st64_b32 v[92:93], v4 offset0:40 offset1:41
	ds_read2st64_b32 v[94:95], v4 offset0:42 offset1:43
	ds_read2st64_b32 v[56:57], v4 offset0:44 offset1:45
	ds_read2st64_b32 v[58:59], v4 offset0:46 offset1:47
	ds_read2st64_b32 v[50:51], v4 offset0:48 offset1:49
	ds_read2st64_b32 v[52:53], v4 offset0:50 offset1:51
	ds_read2st64_b32 v[44:45], v4 offset0:52 offset1:53
	ds_read2st64_b32 v[46:47], v4 offset0:54 offset1:55
	ds_read2st64_b32 v[32:33], v4 offset0:56 offset1:57
	ds_read2st64_b32 v[42:43], v4 offset0:58 offset1:59
	ds_read2st64_b32 v[16:17], v4 offset0:60 offset1:61
	ds_read_b32 v4, v4 offset:15872
	ds_read_b32 v5, v0
	v_lshlrev_b32_e32 v0, 1, v181
	s_mov_b32 s0, 0xf800000
	s_waitcnt lgkmcnt(0)
	v_pk_fma_f32 v[8:9], v[14:15], v[4:5], v[2:3] op_sel_hi:[0,1,1] neg_lo:[1,0,0] neg_hi:[1,0,0]
	v_lshlrev_b64 v[2:3], 11, v[166:167]
	v_lshl_add_u64 v[2:3], s[10:11], 0, v[2:3]
	v_lshlrev_b32_e32 v15, 2, v181
	v_lshl_add_u64 v[2:3], s[26:27], 1, v[2:3]
	v_pk_fma_f32 v[88:89], v[132:133], v[14:15], v[88:89] op_sel_hi:[1,0,1] neg_lo:[1,0,0] neg_hi:[1,0,0]
	v_lshl_add_u64 v[6:7], v[2:3], 0, v[0:1]
	v_mul_f32_e32 v0, v89, v89
	v_pk_fma_f32 v[90:91], v[134:135], v[14:15], v[90:91] op_sel_hi:[1,0,1] neg_lo:[1,0,0] neg_hi:[1,0,0]
	v_pk_fma_f32 v[132:133], v[88:89], v[88:89], v[0:1] op_sel_hi:[1,1,0]
	v_mul_f32_e32 v0, v91, v91
	v_pk_fma_f32 v[132:133], v[90:91], v[90:91], v[132:133]
	v_pk_fma_f32 v[84:85], v[128:129], v[14:15], v[84:85] op_sel_hi:[1,0,1] neg_lo:[1,0,0] neg_hi:[1,0,0]
	v_pk_add_f32 v[132:133], v[0:1], v[132:133] op_sel_hi:[0,1]
	v_pk_fma_f32 v[128:129], v[84:85], v[84:85], v[132:133]
	v_mul_f32_e32 v0, v85, v85
	v_pk_fma_f32 v[86:87], v[14:15], v[130:131], v[86:87] op_sel_hi:[0,1,1] neg_lo:[1,0,0] neg_hi:[1,0,0]
	v_pk_add_f32 v[128:129], v[0:1], v[128:129] op_sel_hi:[0,1]
	v_pk_fma_f32 v[128:129], v[86:87], v[86:87], v[128:129]
	v_mul_f32_e32 v0, v87, v87
	v_pk_add_f32 v[128:129], v[0:1], v[128:129] op_sel_hi:[0,1]
	v_pk_fma_f32 v[80:81], v[14:15], v[124:125], v[80:81] op_sel_hi:[0,1,1] neg_lo:[1,0,0] neg_hi:[1,0,0]
	v_pk_fma_f32 v[124:125], v[80:81], v[80:81], v[128:129]
	v_mul_f32_e32 v0, v81, v81
	v_pk_fma_f32 v[82:83], v[14:15], v[126:127], v[82:83] op_sel_hi:[0,1,1] neg_lo:[1,0,0] neg_hi:[1,0,0]
	v_pk_add_f32 v[124:125], v[0:1], v[124:125] op_sel_hi:[0,1]
	v_pk_fma_f32 v[124:125], v[82:83], v[82:83], v[124:125]
	v_mul_f32_e32 v0, v83, v83
	v_pk_add_f32 v[124:125], v[0:1], v[124:125] op_sel_hi:[0,1]
	v_pk_fma_f32 v[76:77], v[14:15], v[120:121], v[76:77] op_sel_hi:[0,1,1] neg_lo:[1,0,0] neg_hi:[1,0,0]
	v_pk_fma_f32 v[120:121], v[76:77], v[76:77], v[124:125]
	v_mul_f32_e32 v0, v77, v77
	v_pk_fma_f32 v[78:79], v[14:15], v[122:123], v[78:79] op_sel_hi:[0,1,1] neg_lo:[1,0,0] neg_hi:[1,0,0]
	v_pk_add_f32 v[120:121], v[0:1], v[120:121] op_sel_hi:[0,1]
	v_pk_fma_f32 v[120:121], v[78:79], v[78:79], v[120:121]
	v_mul_f32_e32 v0, v79, v79
	v_pk_add_f32 v[120:121], v[0:1], v[120:121] op_sel_hi:[0,1]
	v_pk_fma_f32 v[72:73], v[14:15], v[116:117], v[72:73] op_sel_hi:[0,1,1] neg_lo:[1,0,0] neg_hi:[1,0,0]
	v_pk_fma_f32 v[116:117], v[72:73], v[72:73], v[120:121]
	v_mul_f32_e32 v0, v73, v73
	v_pk_fma_f32 v[74:75], v[14:15], v[118:119], v[74:75] op_sel_hi:[0,1,1] neg_lo:[1,0,0] neg_hi:[1,0,0]
	v_pk_add_f32 v[116:117], v[0:1], v[116:117] op_sel_hi:[0,1]
	v_pk_fma_f32 v[116:117], v[74:75], v[74:75], v[116:117]
	v_mul_f32_e32 v0, v75, v75
	v_pk_add_f32 v[116:117], v[0:1], v[116:117] op_sel_hi:[0,1]
	v_pk_fma_f32 v[68:69], v[14:15], v[112:113], v[68:69] op_sel_hi:[0,1,1] neg_lo:[1,0,0] neg_hi:[1,0,0]
	v_pk_fma_f32 v[112:113], v[68:69], v[68:69], v[116:117]
	v_mul_f32_e32 v0, v69, v69
	v_pk_fma_f32 v[70:71], v[14:15], v[114:115], v[70:71] op_sel_hi:[0,1,1] neg_lo:[1,0,0] neg_hi:[1,0,0]
	v_pk_add_f32 v[112:113], v[0:1], v[112:113] op_sel_hi:[0,1]
	v_pk_fma_f32 v[112:113], v[70:71], v[70:71], v[112:113]
	v_mul_f32_e32 v0, v71, v71
	v_pk_add_f32 v[112:113], v[0:1], v[112:113] op_sel_hi:[0,1]
	v_pk_fma_f32 v[64:65], v[14:15], v[108:109], v[64:65] op_sel_hi:[0,1,1] neg_lo:[1,0,0] neg_hi:[1,0,0]
	v_pk_fma_f32 v[108:109], v[64:65], v[64:65], v[112:113]
	v_mul_f32_e32 v0, v65, v65
	v_pk_fma_f32 v[66:67], v[14:15], v[110:111], v[66:67] op_sel_hi:[0,1,1] neg_lo:[1,0,0] neg_hi:[1,0,0]
; __device__ __forceinline__ float swapsum(float m) { auto rr = __builtin_amdgcn_permlane32_swap(__float_as_uint(m), __float_as_uint(m), false, false); return __uint_as_float(rr[0]) + __uint_as_float(rr[1]); }
; template <int MODE> __device__ __forceinline__ void attn_unit4(LAS unsigned char* lds, const int uidx, const AttnArgs& A) {
;     ...
;             for (int d = 0; d < NDB; ++d)
; #pragma unroll
;                 for (int r = 0; r < 16; ++r) { const float v = o[d][r] - lam * X[(qg * 64 + d * 16 + r) * 64 + lane]; o[d][r] = v; ss += v * v; }
;             ss = swapsum(ss);
;             const float rs = (1.0f / sqrtf(ss * (1.0f / 128.0f) + EPSN)) * (1.0f - A.lam_init);
	v_pk_add_f32 v[108:109], v[0:1], v[108:109] op_sel_hi:[0,1]
	v_pk_fma_f32 v[108:109], v[66:67], v[66:67], v[108:109]
	v_mul_f32_e32 v0, v67, v67
	v_pk_add_f32 v[108:109], v[0:1], v[108:109] op_sel_hi:[0,1]
	v_pk_fma_f32 v[60:61], v[14:15], v[104:105], v[60:61] op_sel_hi:[0,1,1] neg_lo:[1,0,0] neg_hi:[1,0,0]
	v_pk_fma_f32 v[104:105], v[60:61], v[60:61], v[108:109]
	v_mul_f32_e32 v0, v61, v61
	v_pk_fma_f32 v[62:63], v[14:15], v[106:107], v[62:63] op_sel_hi:[0,1,1] neg_lo:[1,0,0] neg_hi:[1,0,0]
	v_pk_add_f32 v[104:105], v[0:1], v[104:105] op_sel_hi:[0,1]
	v_pk_fma_f32 v[104:105], v[62:63], v[62:63], v[104:105]
	v_mul_f32_e32 v0, v63, v63
	v_pk_add_f32 v[104:105], v[0:1], v[104:105] op_sel_hi:[0,1]
	v_pk_fma_f32 v[48:49], v[14:15], v[100:101], v[48:49] op_sel_hi:[0,1,1] neg_lo:[1,0,0] neg_hi:[1,0,0]
	v_pk_fma_f32 v[100:101], v[48:49], v[48:49], v[104:105]
	v_mul_f32_e32 v0, v49, v49
	v_pk_fma_f32 v[54:55], v[14:15], v[102:103], v[54:55] op_sel_hi:[0,1,1] neg_lo:[1,0,0] neg_hi:[1,0,0]
	v_pk_add_f32 v[100:101], v[0:1], v[100:101] op_sel_hi:[0,1]
	v_pk_fma_f32 v[100:101], v[54:55], v[54:55], v[100:101]
	v_mul_f32_e32 v0, v55, v55
	v_pk_add_f32 v[100:101], v[0:1], v[100:101] op_sel_hi:[0,1]
	v_pk_fma_f32 v[38:39], v[14:15], v[96:97], v[38:39] op_sel_hi:[0,1,1] neg_lo:[1,0,0] neg_hi:[1,0,0]
	v_pk_fma_f32 v[96:97], v[38:39], v[38:39], v[100:101]
	v_mul_f32_e32 v0, v39, v39
	v_pk_fma_f32 v[40:41], v[14:15], v[98:99], v[40:41] op_sel_hi:[0,1,1] neg_lo:[1,0,0] neg_hi:[1,0,0]
	v_pk_add_f32 v[96:97], v[0:1], v[96:97] op_sel_hi:[0,1]
	v_pk_fma_f32 v[96:97], v[40:41], v[40:41], v[96:97]
	v_mul_f32_e32 v0, v41, v41
	v_pk_add_f32 v[96:97], v[0:1], v[96:97] op_sel_hi:[0,1]
	v_pk_fma_f32 v[34:35], v[14:15], v[92:93], v[34:35] op_sel_hi:[0,1,1] neg_lo:[1,0,0] neg_hi:[1,0,0]
	v_pk_fma_f32 v[92:93], v[34:35], v[34:35], v[96:97]
	v_mul_f32_e32 v0, v35, v35
	v_pk_fma_f32 v[36:37], v[14:15], v[94:95], v[36:37] op_sel_hi:[0,1,1] neg_lo:[1,0,0] neg_hi:[1,0,0]
	v_pk_add_f32 v[92:93], v[0:1], v[92:93] op_sel_hi:[0,1]
	v_pk_fma_f32 v[92:93], v[36:37], v[36:37], v[92:93]
	v_mul_f32_e32 v0, v37, v37
	v_pk_add_f32 v[92:93], v[0:1], v[92:93] op_sel_hi:[0,1]
	v_pk_fma_f32 v[56:57], v[14:15], v[56:57], v[26:27] op_sel_hi:[0,1,1] neg_lo:[1,0,0] neg_hi:[1,0,0]
	v_pk_fma_f32 v[26:27], v[56:57], v[56:57], v[92:93]
	v_mul_f32_e32 v0, v57, v57
	v_pk_fma_f32 v[30:31], v[14:15], v[58:59], v[30:31] op_sel_hi:[0,1,1] neg_lo:[1,0,0] neg_hi:[1,0,0]
	v_pk_add_f32 v[26:27], v[0:1], v[26:27] op_sel_hi:[0,1]
	v_pk_fma_f32 v[26:27], v[30:31], v[30:31], v[26:27]
	v_mul_f32_e32 v0, v31, v31
	v_pk_add_f32 v[58:59], v[0:1], v[26:27] op_sel_hi:[0,1]
	v_pk_fma_f32 v[24:25], v[14:15], v[50:51], v[24:25] op_sel_hi:[0,1,1] neg_lo:[1,0,0] neg_hi:[1,0,0]
	v_pk_fma_f32 v[26:27], v[14:15], v[52:53], v[28:29] op_sel_hi:[0,1,1] neg_lo:[1,0,0] neg_hi:[1,0,0]
	v_pk_fma_f32 v[28:29], v[24:25], v[24:25], v[58:59]
	v_mul_f32_e32 v0, v25, v25
	v_pk_add_f32 v[28:29], v[0:1], v[28:29] op_sel_hi:[0,1]
	v_pk_fma_f32 v[28:29], v[26:27], v[26:27], v[28:29]
	v_mul_f32_e32 v0, v27, v27
	v_pk_add_f32 v[28:29], v[0:1], v[28:29] op_sel_hi:[0,1]
	v_pk_fma_f32 v[20:21], v[14:15], v[44:45], v[20:21] op_sel_hi:[0,1,1] neg_lo:[1,0,0] neg_hi:[1,0,0]
	v_pk_fma_f32 v[28:29], v[20:21], v[20:21], v[28:29]
	v_mul_f32_e32 v0, v21, v21
	v_pk_fma_f32 v[22:23], v[14:15], v[46:47], v[22:23] op_sel_hi:[0,1,1] neg_lo:[1,0,0] neg_hi:[1,0,0]
	v_pk_add_f32 v[28:29], v[0:1], v[28:29] op_sel_hi:[0,1]
	v_pk_fma_f32 v[28:29], v[22:23], v[22:23], v[28:29]
	v_mul_f32_e32 v0, v23, v23
	v_pk_add_f32 v[28:29], v[0:1], v[28:29] op_sel_hi:[0,1]
	v_pk_fma_f32 v[18:19], v[14:15], v[32:33], v[18:19] op_sel_hi:[0,1,1] neg_lo:[1,0,0] neg_hi:[1,0,0]
	v_pk_fma_f32 v[28:29], v[18:19], v[18:19], v[28:29]
	v_mul_f32_e32 v0, v19, v19
	v_pk_fma_f32 v[12:13], v[14:15], v[42:43], v[12:13] op_sel_hi:[0,1,1] neg_lo:[1,0,0] neg_hi:[1,0,0]
	v_pk_add_f32 v[28:29], v[0:1], v[28:29] op_sel_hi:[0,1]
	v_pk_fma_f32 v[28:29], v[12:13], v[12:13], v[28:29]
	v_mul_f32_e32 v0, v13, v13
	v_pk_add_f32 v[28:29], v[0:1], v[28:29] op_sel_hi:[0,1]
	v_pk_fma_f32 v[10:11], v[14:15], v[16:17], v[10:11] op_sel_hi:[0,1,1] neg_lo:[1,0,0] neg_hi:[1,0,0]
	v_pk_fma_f32 v[16:17], v[10:11], v[10:11], v[28:29]
	v_mul_f32_e32 v0, v11, v11
	v_pk_add_f32 v[16:17], v[0:1], v[16:17] op_sel_hi:[0,1]
	v_pk_fma_f32 v[16:17], v[8:9], v[8:9], v[16:17]
	v_mul_f32_e32 v0, v9, v9
	v_pk_add_f32 v[16:17], v[0:1], v[16:17] op_sel_hi:[0,1]
	v_mov_b32_e32 v0, v16
	s_nop 1
	v_permlane32_swap_b32_e32 v16, v0
	v_add_f32_e32 v0, v16, v0
	v_fmamk_f32 v0, v0, 0x3c000000, v218
	v_cmp_gt_f32_e32 vcc, s0, v0
	v_mul_f32_e32 v14, 0x4f800000, v0
	s_nop 0
	v_cndmask_b32_e32 v0, v0, v14, vcc
	v_sqrt_f32_e32 v14, v0
	s_nop 0
	v_add_u32_e32 v16, -1, v14
	v_fma_f32 v17, -v16, v14, v0
	v_cmp_ge_f32_e64 s[0:1], 0, v17
	v_add_u32_e32 v17, 1, v14
	s_nop 0
	v_cndmask_b32_e64 v16, v14, v16, s[0:1]
	v_fma_f32 v14, -v17, v14, v0
	v_cmp_lt_f32_e64 s[0:1], 0, v14
	s_nop 1
	v_cndmask_b32_e64 v14, v16, v17, s[0:1]
	v_mul_f32_e32 v16, 0x37800000, v14
	v_cndmask_b32_e32 v14, v14, v16, vcc
	v_mov_b32_e32 v16, 0x260
	v_cmp_class_f32_e32 vcc, v0, v16
	s_nop 1
	v_cndmask_b32_e32 v0, v14, v0, vcc
	v_div_scale_f32 v14, s[0:1], v0, v0, 1.0
	v_rcp_f32_e32 v16, v14
	s_nop 0
	v_fma_f32 v17, -v14, v16, 1.0
	v_fmac_f32_e32 v16, v17, v16
	v_div_scale_f32 v17, vcc, 1.0, v0, 1.0
	v_mul_f32_e32 v28, v17, v16
	v_fma_f32 v29, -v14, v28, v17
	v_fmac_f32_e32 v28, v29, v16
	v_fma_f32 v14, -v14, v28, v17
	v_div_fmas_f32 v14, v14, v16, v28
	v_div_fixup_f32 v0, v14, v0, 1.0
	v_mul_f32_e32 v0, v191, v0
	v_pk_mul_f32 v[16:17], v[88:89], v[0:1] op_sel_hi:[1,0]
	v_pk_mul_f32 v[12:13], v[12:13], v[0:1] op_sel_hi:[1,0]
	s_waitcnt vmcnt(0)
; #define GAS __attribute__((address_space(1)))
; __device__ __forceinline__ unsigned cvtpk(float lo, float hi) { f32x2_t v = {lo, hi}; bf16x2_t b = __builtin_convertvector(v, bf16x2_t); return __builtin_bit_cast(unsigned, b); }
; template <int MODE> __device__ __forceinline__ void attn_unit4(LAS unsigned char* lds, const int uidx, const AttnArgs& A) {
;     ...
;             GAS bf16_t* op = (GAS bf16_t*)A.O + orow * DM + hx * 128 + 4 * hi;
; #pragma unroll
;             for (int d = 0; d < NDB; ++d)
; #pragma unroll
;                 for (int g4 = 0; g4 < 4; ++g4) {
;                     const f32x4 gv = *(const GAS f32x4*)((const GAS float*)A.gsub + d * 32 + 8 * g4 + 4 * hi);
;                     u32x2 w; w.x = cvtpk(o[d][4 * g4] * rs * gv[0], o[d][4 * g4 + 1] * rs * gv[1]); w.y = cvtpk(o[d][4 * g4 + 2] * rs * gv[2], o[d][4 * g4 + 3] * rs * gv[3]);
;                     *(GAS u32x2*)(op + d * 32 + 8 * g4) = w;
;                 }
	v_pk_mul_f32 v[2:3], v[136:137], v[16:17]
	v_pk_mul_f32 v[16:17], v[90:91], v[0:1] op_sel_hi:[1,0]
	v_cvt_pk_bf16_f32 v2, v2, v3
	v_pk_mul_f32 v[4:5], v[138:139], v[16:17]
	v_pk_mul_f32 v[16:17], v[84:85], v[0:1] op_sel_hi:[1,0]
	v_cvt_pk_bf16_f32 v3, v4, v5
	global_store_dwordx2 v[6:7], v[2:3], off
	v_pk_mul_f32 v[10:11], v[10:11], v[0:1] op_sel_hi:[1,0]
	v_pk_mul_f32 v[8:9], v[8:9], v[0:1] op_sel_hi:[1,0]
	v_pk_mul_f32 v[2:3], v[140:141], v[16:17]
	v_pk_mul_f32 v[16:17], v[86:87], v[0:1] op_sel_hi:[1,0]
	v_cvt_pk_bf16_f32 v2, v2, v3
	v_pk_mul_f32 v[4:5], v[142:143], v[16:17]
	v_pk_mul_f32 v[16:17], v[80:81], v[0:1] op_sel_hi:[1,0]
	v_cvt_pk_bf16_f32 v3, v4, v5
	global_store_dwordx2 v[6:7], v[2:3], off offset:16
	v_pk_mul_f32 v[2:3], v[144:145], v[16:17]
	v_pk_mul_f32 v[16:17], v[82:83], v[0:1] op_sel_hi:[1,0]
	v_cvt_pk_bf16_f32 v2, v2, v3
	v_pk_mul_f32 v[4:5], v[146:147], v[16:17]
	v_pk_mul_f32 v[16:17], v[76:77], v[0:1] op_sel_hi:[1,0]
	v_cvt_pk_bf16_f32 v3, v4, v5
	global_store_dwordx2 v[6:7], v[2:3], off offset:32
	v_pk_mul_f32 v[2:3], v[148:149], v[16:17]
	v_pk_mul_f32 v[16:17], v[78:79], v[0:1] op_sel_hi:[1,0]
	v_cvt_pk_bf16_f32 v2, v2, v3
	v_pk_mul_f32 v[4:5], v[150:151], v[16:17]
	v_pk_mul_f32 v[16:17], v[72:73], v[0:1] op_sel_hi:[1,0]
	v_cvt_pk_bf16_f32 v3, v4, v5
	global_store_dwordx2 v[6:7], v[2:3], off offset:48
	v_pk_mul_f32 v[2:3], v[16:17], v[152:153]
	v_pk_mul_f32 v[16:17], v[74:75], v[0:1] op_sel_hi:[1,0]
	v_cvt_pk_bf16_f32 v2, v2, v3
	v_pk_mul_f32 v[4:5], v[16:17], v[154:155]
	v_pk_mul_f32 v[16:17], v[68:69], v[0:1] op_sel_hi:[1,0]
	v_cvt_pk_bf16_f32 v3, v4, v5
	global_store_dwordx2 v[6:7], v[2:3], off offset:64
	v_pk_mul_f32 v[2:3], v[16:17], v[156:157]
	v_pk_mul_f32 v[16:17], v[70:71], v[0:1] op_sel_hi:[1,0]
	v_cvt_pk_bf16_f32 v2, v2, v3
	v_pk_mul_f32 v[4:5], v[16:17], v[158:159]
	v_pk_mul_f32 v[16:17], v[64:65], v[0:1] op_sel_hi:[1,0]
	v_cvt_pk_bf16_f32 v3, v4, v5
	global_store_dwordx2 v[6:7], v[2:3], off offset:80
	v_pk_mul_f32 v[2:3], v[16:17], v[160:161]
	v_pk_mul_f32 v[16:17], v[66:67], v[0:1] op_sel_hi:[1,0]
	v_cvt_pk_bf16_f32 v2, v2, v3
	v_pk_mul_f32 v[4:5], v[16:17], v[162:163]
	v_pk_mul_f32 v[16:17], v[60:61], v[0:1] op_sel_hi:[1,0]
	v_cvt_pk_bf16_f32 v3, v4, v5
	global_store_dwordx2 v[6:7], v[2:3], off offset:96
	v_pk_mul_f32 v[2:3], v[16:17], v[192:193]
	v_pk_mul_f32 v[16:17], v[62:63], v[0:1] op_sel_hi:[1,0]
	v_cvt_pk_bf16_f32 v2, v2, v3
	v_pk_mul_f32 v[4:5], v[16:17], v[194:195]
	v_pk_mul_f32 v[16:17], v[48:49], v[0:1] op_sel_hi:[1,0]
	v_cvt_pk_bf16_f32 v3, v4, v5
	global_store_dwordx2 v[6:7], v[2:3], off offset:112
	v_pk_mul_f32 v[2:3], v[16:17], v[196:197]
	v_pk_mul_f32 v[16:17], v[54:55], v[0:1] op_sel_hi:[1,0]
	v_cvt_pk_bf16_f32 v2, v2, v3
	v_pk_mul_f32 v[4:5], v[16:17], v[198:199]
	v_pk_mul_f32 v[16:17], v[38:39], v[0:1] op_sel_hi:[1,0]
	v_cvt_pk_bf16_f32 v3, v4, v5
	global_store_dwordx2 v[6:7], v[2:3], off offset:128
	v_pk_mul_f32 v[2:3], v[16:17], v[200:201]
	v_pk_mul_f32 v[16:17], v[40:41], v[0:1] op_sel_hi:[1,0]
	v_cvt_pk_bf16_f32 v2, v2, v3
	v_pk_mul_f32 v[4:5], v[16:17], v[202:203]
	v_pk_mul_f32 v[16:17], v[34:35], v[0:1] op_sel_hi:[1,0]
	v_cvt_pk_bf16_f32 v3, v4, v5
	global_store_dwordx2 v[6:7], v[2:3], off offset:144
	v_pk_mul_f32 v[2:3], v[16:17], v[204:205]
	v_pk_mul_f32 v[16:17], v[36:37], v[0:1] op_sel_hi:[1,0]
	v_cvt_pk_bf16_f32 v2, v2, v3
	v_pk_mul_f32 v[4:5], v[16:17], v[206:207]
	v_pk_mul_f32 v[16:17], v[56:57], v[0:1] op_sel_hi:[1,0]
	v_cvt_pk_bf16_f32 v3, v4, v5
	global_store_dwordx2 v[6:7], v[2:3], off offset:160
	v_pk_mul_f32 v[2:3], v[16:17], v[208:209]
	v_pk_mul_f32 v[16:17], v[30:31], v[0:1] op_sel_hi:[1,0]
	v_cvt_pk_bf16_f32 v2, v2, v3
	v_pk_mul_f32 v[4:5], v[16:17], v[210:211]
	v_pk_mul_f32 v[16:17], v[24:25], v[0:1] op_sel_hi:[1,0]
	v_cvt_pk_bf16_f32 v3, v4, v5
	global_store_dwordx2 v[6:7], v[2:3], off offset:176
	v_pk_mul_f32 v[2:3], v[16:17], v[212:213]
	v_pk_mul_f32 v[16:17], v[26:27], v[0:1] op_sel_hi:[1,0]
	v_cvt_pk_bf16_f32 v2, v2, v3
	v_pk_mul_f32 v[4:5], v[16:17], v[214:215]
	v_pk_mul_f32 v[16:17], v[20:21], v[0:1] op_sel_hi:[1,0]
	v_cvt_pk_bf16_f32 v3, v4, v5
	global_store_dwordx2 v[6:7], v[2:3], off offset:192
	v_pk_mul_f32 v[2:3], v[16:17], v[220:221]
	v_pk_mul_f32 v[16:17], v[22:23], v[0:1] op_sel_hi:[1,0]
	v_cvt_pk_bf16_f32 v2, v2, v3
	v_pk_mul_f32 v[4:5], v[16:17], v[222:223]
	v_pk_mul_f32 v[16:17], v[18:19], v[0:1] op_sel_hi:[1,0]
	v_cvt_pk_bf16_f32 v3, v4, v5
	global_store_dwordx2 v[6:7], v[2:3], off offset:208
	v_pk_mul_f32 v[2:3], v[16:17], v[228:229]
	v_pk_mul_f32 v[4:5], v[12:13], v[230:231]
	v_cvt_pk_bf16_f32 v2, v2, v3
	v_cvt_pk_bf16_f32 v3, v4, v5
	global_store_dwordx2 v[6:7], v[2:3], off offset:224
	v_pk_mul_f32 v[2:3], v[10:11], v[232:233]
	v_pk_mul_f32 v[4:5], v[8:9], v[234:235]
	v_cvt_pk_bf16_f32 v2, v2, v3
	v_cvt_pk_bf16_f32 v3, v4, v5
	global_store_dwordx2 v[6:7], v[2:3], off offset:240
	s_branch .LBB0_908
.Lgs_pre:
	v_lshlrev_b32_e32 v250, 2, v181
	global_load_dwordx4 v[136:139], v250, s[60:61]
	global_load_dwordx4 v[140:143], v250, s[60:61] offset:32
	global_load_dwordx4 v[144:147], v250, s[60:61] offset:64
	global_load_dwordx4 v[148:151], v250, s[60:61] offset:96
	global_load_dwordx4 v[152:155], v250, s[60:61] offset:128
	global_load_dwordx4 v[156:159], v250, s[60:61] offset:160
	global_load_dwordx4 v[160:163], v250, s[60:61] offset:192
	global_load_dwordx4 v[192:195], v250, s[60:61] offset:224
	global_load_dwordx4 v[196:199], v250, s[60:61] offset:256
	global_load_dwordx4 v[200:203], v250, s[60:61] offset:288
	global_load_dwordx4 v[204:207], v250, s[60:61] offset:320
	global_load_dwordx4 v[208:211], v250, s[60:61] offset:352
	global_load_dwordx4 v[212:215], v250, s[60:61] offset:384
	global_load_dwordx4 v[220:223], v250, s[60:61] offset:416
	global_load_dwordx4 v[228:231], v250, s[60:61] offset:448
	global_load_dwordx4 v[232:235], v250, s[60:61] offset:480
	s_branch .LBB0_1005
